# phase 0 weight-transpose tiles: the 16 row loads of a tile issued back to back instead of one load + full drain per loop iteration
# speedup vs baseline: 1.0220x; 1.0033x over previous
.Lp0cv_entry:
	v_mov_b32_e32 v131, 0
	v_mov_b32_e32 v147, 0
	v_mov_b32_e32 v166, 0
	v_mov_b32_e32 v167, 0
	v_mov_b32_e32 v168, 0
	v_mov_b32_e32 v169, 0
	v_mov_b32_e32 v170, 0
	v_mov_b32_e32 v171, 0
	v_mov_b32_e32 v172, 0
	v_mov_b32_e32 v173, 0
	v_mov_b32_e32 v174, 0
	v_mov_b32_e32 v175, 0
	v_mov_b32_e32 v176, 0
	v_mov_b32_e32 v177, 0
	v_mov_b32_e32 v178, 0
	v_mov_b32_e32 v179, 0
	s_mov_b64 s[98:99], 0xa8c0
	s_mov_b64 s[20:21], exec
	s_and_saveexec_b64 s[4:5], s[0:1]
	global_load_dword v131, v[4:5], off
	v_lshl_add_u64 v[4:5], v[4:5], 0, s[98:99]
	global_load_dword v147, v[4:5], off
	v_lshl_add_u64 v[4:5], v[4:5], 0, s[98:99]
	global_load_dword v166, v[4:5], off
	v_lshl_add_u64 v[4:5], v[4:5], 0, s[98:99]
	global_load_dword v167, v[4:5], off
	v_lshl_add_u64 v[4:5], v[4:5], 0, s[98:99]
	global_load_dword v168, v[4:5], off
	v_lshl_add_u64 v[4:5], v[4:5], 0, s[98:99]
	global_load_dword v169, v[4:5], off
	v_lshl_add_u64 v[4:5], v[4:5], 0, s[98:99]
	global_load_dword v170, v[4:5], off
	v_lshl_add_u64 v[4:5], v[4:5], 0, s[98:99]
	global_load_dword v171, v[4:5], off
	v_lshl_add_u64 v[4:5], v[4:5], 0, s[98:99]
	global_load_dword v172, v[4:5], off
	v_lshl_add_u64 v[4:5], v[4:5], 0, s[98:99]
	global_load_dword v173, v[4:5], off
	v_lshl_add_u64 v[4:5], v[4:5], 0, s[98:99]
	global_load_dword v174, v[4:5], off
	v_lshl_add_u64 v[4:5], v[4:5], 0, s[98:99]
	global_load_dword v175, v[4:5], off
	v_lshl_add_u64 v[4:5], v[4:5], 0, s[98:99]
	global_load_dword v176, v[4:5], off
	v_lshl_add_u64 v[4:5], v[4:5], 0, s[98:99]
	global_load_dword v177, v[4:5], off
	v_lshl_add_u64 v[4:5], v[4:5], 0, s[98:99]
	global_load_dword v178, v[4:5], off
	v_lshl_add_u64 v[4:5], v[4:5], 0, s[98:99]
	global_load_dword v179, v[4:5], off
	v_lshl_add_u64 v[4:5], v[4:5], 0, s[98:99]
	s_or_b64 exec, exec, s[4:5]
	s_waitcnt vmcnt(0)
	ds_write_b32 v6, v131 offset:0
	ds_write_b32 v6, v147 offset:1040
	ds_write_b32 v6, v166 offset:2080
	ds_write_b32 v6, v167 offset:3120
	ds_write_b32 v6, v168 offset:4160
	ds_write_b32 v6, v169 offset:5200
	ds_write_b32 v6, v170 offset:6240
	ds_write_b32 v6, v171 offset:7280
	ds_write_b32 v6, v172 offset:8320
	ds_write_b32 v6, v173 offset:9360
	ds_write_b32 v6, v174 offset:10400
	ds_write_b32 v6, v175 offset:11440
	ds_write_b32 v6, v176 offset:12480
	ds_write_b32 v6, v177 offset:13520
	ds_write_b32 v6, v178 offset:14560
	ds_write_b32 v6, v179 offset:15600
	v_add_u32_e32 v6, 0x4100, v6
	v_add_u32_e32 v3, 64, v3
	s_branch .LBB0_52
